# v16 + nt hint on last-use residual loads in the w_o and down epilogues
# baseline (speedup 1.0000x reference)
; __device__ __forceinline__ unsigned cvtpk(float lo, float hi) { f32x2_t v = {lo, hi}; f16x2_t b = __builtin_convertvector(v, f16x2_t); return __builtin_bit_cast(unsigned, b); }
; __device__ __forceinline__ float bflo(unsigned w) { const f16x2_t b = __builtin_bit_cast(f16x2_t, w); return (float)b[0]; }
; __device__ __forceinline__ float bfhi(unsigned w) { const f16x2_t b = __builtin_bit_cast(f16x2_t, w); return (float)b[1]; }
;     __device__ __forceinline__ void operator()(const f32x4 (&acc)[2][2][4][2], const Unit& u, int wr, int wc, int fr, int fq) const {
;         const int row0 = u.pm * BM + wr * 64 + fr, col0 = u.pn * BM + wc * 32 + 4 * fq;
; #pragma unroll
;         for (int ai = 0; ai < 2; ++ai) { u32x2 bs[4][2][2];
; #pragma unroll
;             for (int m = 0; m < 4; ++m)
; #pragma unroll
;                 for (int bj = 0; bj < 2; ++bj)
; #pragma unroll
;                     for (int n = 0; n < 2; ++n) bs[m][bj][n] = *(const u32x2*)(xres + (size_t)(row0 + ai * HALF + m * 16) * 1024 + col0 + bj * HALF + n * 16);
; #pragma unroll
;             for (int m = 0; m < 4; ++m) { const int row = row0 + ai * HALF + m * 16; const size_t off = (size_t)row * 1024 + col0; float ss = 0.f;
; #pragma unroll
;                 for (int bj = 0; bj < 2; ++bj)
; #pragma unroll
;                     for (int n = 0; n < 2; ++n) { const size_t o2 = off + bj * HALF + n * 16; const u32x2 b = bs[m][bj][n];
;                         const f32x4 o = (f32x4){bflo(b.x), bfhi(b.x), bflo(b.y), bfhi(b.y)} + acc[ai][bj][m][n];
;                         ss += (o[0] * o[0] + o[1] * o[1]) + (o[2] * o[2] + o[3] * o[3]);
;                         u32x2 w; w.x = cvtpk(o[0], o[1]); w.y = cvtpk(o[2], o[3]); *(u32x2*)(xres + o2) = w; }
;                 ss += __shfl_xor(ss, 16); ss += __shfl_xor(ss, 32);
;                 if (fq == 0) part[(size_t)row * 16 + u.pn * 4 + wc] = ss; }
.LBB0_852:
	v_and_b32_e32 v140, 64, v233
	v_xor_b32_e32 v139, 16, v233
	v_add_u32_e32 v140, 64, v140
	v_cmp_lt_i32_e32 vcc, v139, v140
	v_lshl_or_b32 v136, s24, 8, v207
	v_lshl_add_u32 v138, s54, 8, v179
	v_cndmask_b32_e32 v139, v233, v139, vcc
	v_lshlrev_b32_e32 v210, 2, v139
	v_xor_b32_e32 v139, 32, v233
	v_cmp_lt_i32_e32 vcc, v139, v140
	v_ashrrev_i32_e32 v137, 31, v136
	v_lshlrev_b64 v[202:203], 1, v[136:137]
	v_cndmask_b32_e32 v139, v233, v139, vcc
	v_lshlrev_b32_e32 v209, 2, v139
	v_ashrrev_i32_e32 v139, 31, v138
	v_lshl_add_u64 v[140:141], s[18:19], 0, v[202:203]
	v_lshlrev_b64 v[204:205], 11, v[138:139]
	v_lshl_add_u64 v[142:143], v[140:141], 0, v[204:205]
	global_load_dwordx2 v[172:173], v[142:143], off nt
	global_load_dwordx2 v[200:201], v[142:143], off offset:32 nt
	global_load_dwordx2 v[198:199], v[142:143], off offset:256 nt
	global_load_dwordx2 v[196:197], v[142:143], off offset:288 nt
	v_or_b32_e32 v180, 16, v138
	v_ashrrev_i32_e32 v181, 31, v180
	v_or_b32_e32 v144, 32, v138
	v_lshlrev_b64 v[192:193], 11, v[180:181]
	v_ashrrev_i32_e32 v145, 31, v144
	v_lshl_add_u64 v[142:143], v[140:141], 0, v[192:193]
	v_lshlrev_b64 v[182:183], 11, v[144:145]
	global_load_dwordx2 v[194:195], v[142:143], off nt
	global_load_dwordx2 v[190:191], v[142:143], off offset:32 nt
	global_load_dwordx2 v[188:189], v[142:143], off offset:256 nt
	global_load_dwordx2 v[186:187], v[142:143], off offset:288 nt
	v_lshl_add_u64 v[142:143], v[140:141], 0, v[182:183]
	global_load_dwordx2 v[184:185], v[142:143], off nt
	global_load_dwordx2 v[160:161], v[142:143], off offset:32 nt
	global_load_dwordx2 v[156:157], v[142:143], off offset:256 nt
	global_load_dwordx2 v[152:153], v[142:143], off offset:288 nt
	v_or_b32_e32 v142, 48, v138
	v_ashrrev_i32_e32 v143, 31, v142
	v_lshlrev_b64 v[148:149], 11, v[142:143]
	v_lshl_add_u64 v[146:147], v[140:141], 0, v[148:149]
	global_load_dwordx2 v[158:159], v[146:147], off nt
	global_load_dwordx2 v[154:155], v[146:147], off offset:32 nt
	global_load_dwordx2 v[150:151], v[146:147], off offset:256 nt
	s_nop 0
	global_load_dwordx2 v[146:147], v[146:147], off offset:288 nt
	s_lshl_b32 s24, s24, 2
	s_ashr_i32 s25, s24, 31
	s_waitcnt vmcnt(0)
	v_cvt_f32_f16_e32 v212, v172
	v_cvt_f32_f16_sdwa v213, v172 dst_sel:DWORD dst_unused:UNUSED_PAD src0_sel:WORD_1
	v_cvt_f32_f16_e32 v172, v173
	v_cvt_f32_f16_sdwa v173, v173 dst_sel:DWORD dst_unused:UNUSED_PAD src0_sel:WORD_1
	v_pk_add_f32 v[126:127], v[126:127], v[212:213]
	v_pk_add_f32 v[128:129], v[128:129], v[172:173]
	v_mul_f32_e32 v172, v127, v127
	v_mul_f32_e32 v173, v129, v129
	v_fmac_f32_e32 v172, v126, v126
	v_fmac_f32_e32 v173, v128, v128
	v_add_f32_e32 v174, v172, v173
	v_cvt_pk_f16_f32 v172, v126, v127
	v_lshl_add_u64 v[126:127], s[18:19], 0, v[204:205]
	v_cvt_pk_f16_f32 v173, v128, v129
	v_lshl_add_u64 v[126:127], v[126:127], 0, v[202:203]
	v_cvt_f32_f16_e32 v128, v200
	v_cvt_f32_f16_sdwa v129, v200 dst_sel:DWORD dst_unused:UNUSED_PAD src0_sel:WORD_1
	global_store_dwordx2 v[126:127], v[172:173], off
	v_cvt_f32_f16_e32 v172, v201
	v_cvt_f32_f16_sdwa v173, v201 dst_sel:DWORD dst_unused:UNUSED_PAD src0_sel:WORD_1
	v_pk_add_f32 v[122:123], v[122:123], v[128:129]
	v_pk_add_f32 v[124:125], v[124:125], v[172:173]
	v_mul_f32_e32 v128, v123, v123
	v_fmac_f32_e32 v128, v122, v122
	v_cvt_pk_f16_f32 v122, v122, v123
	v_cvt_pk_f16_f32 v123, v124, v125
	v_mul_f32_e32 v129, v125, v125
	global_store_dwordx2 v[126:127], v[122:123], off offset:32
	v_cvt_f32_f16_e32 v122, v198
	v_cvt_f32_f16_sdwa v123, v198 dst_sel:DWORD dst_unused:UNUSED_PAD src0_sel:WORD_1
	v_fmac_f32_e32 v129, v124, v124
	v_cvt_f32_f16_e32 v124, v199
	v_cvt_f32_f16_sdwa v125, v199 dst_sel:DWORD dst_unused:UNUSED_PAD src0_sel:WORD_1
	v_pk_add_f32 v[118:119], v[118:119], v[122:123]
	v_add_f32_e32 v128, v128, v129
	v_mul_f32_e32 v122, v119, v119
	v_pk_add_f32 v[120:121], v[120:121], v[124:125]
	v_fmac_f32_e32 v122, v118, v118
	v_mul_f32_e32 v123, v121, v121
	v_cvt_pk_f16_f32 v118, v118, v119
	v_cvt_pk_f16_f32 v119, v120, v121
	v_fmac_f32_e32 v123, v120, v120
	global_store_dwordx2 v[126:127], v[118:119], off offset:256
	v_cvt_f32_f16_e32 v118, v196
	v_cvt_f32_f16_sdwa v119, v196 dst_sel:DWORD dst_unused:UNUSED_PAD src0_sel:WORD_1
	v_cvt_f32_f16_e32 v120, v197
	v_cvt_f32_f16_sdwa v121, v197 dst_sel:DWORD dst_unused:UNUSED_PAD src0_sel:WORD_1
	v_add_f32_e32 v128, v174, v128
	v_pk_add_f32 v[114:115], v[114:115], v[118:119]
	v_add_f32_e32 v122, v122, v123
	v_pk_add_f32 v[116:117], v[116:117], v[120:121]
	v_mul_f32_e32 v118, v115, v115
	v_mul_f32_e32 v119, v117, v117
	v_fmac_f32_e32 v118, v114, v114
	v_fmac_f32_e32 v119, v116, v116
	v_add_f32_e32 v122, v128, v122
	v_add_f32_e32 v118, v118, v119
	v_add_f32_e32 v118, v122, v118
	v_cvt_pk_f16_f32 v114, v114, v115
	v_cvt_pk_f16_f32 v115, v116, v117
	global_store_dwordx2 v[126:127], v[114:115], off offset:288
	ds_bpermute_b32 v114, v210, v118
	s_waitcnt lgkmcnt(0)
	v_add_f32_e32 v114, v118, v114
	ds_bpermute_b32 v115, v209, v114
	s_and_saveexec_b64 s[26:27], s[38:39]
	v_readlane_b32 s76, v253, 5
	v_readlane_b32 s77, v253, 6
	v_readlane_b32 s78, v253, 7
	v_readlane_b32 s79, v253, 8
	s_cbranch_execz .LBB0_854
	s_waitcnt lgkmcnt(0)
	v_add_f32_e32 v116, v114, v115
	v_lshlrev_b64 v[114:115], 6, v[138:139]
	v_lshl_add_u64 v[114:115], s[20:21], 0, v[114:115]
	v_lshl_add_u64 v[114:115], s[24:25], 2, v[114:115]
	s_lshl_b32 s70, s55, 2
	v_lshl_add_u64 v[114:115], v[114:115], 0, s[70:71]
	global_store_dword v[114:115], v116, off

; __device__ __forceinline__ unsigned cvtpk(float lo, float hi) { f32x2_t v = {lo, hi}; f16x2_t b = __builtin_convertvector(v, f16x2_t); return __builtin_bit_cast(unsigned, b); }
; __device__ __forceinline__ float bflo(unsigned w) { const f16x2_t b = __builtin_bit_cast(f16x2_t, w); return (float)b[0]; }
; __device__ __forceinline__ float bfhi(unsigned w) { const f16x2_t b = __builtin_bit_cast(f16x2_t, w); return (float)b[1]; }
;     __device__ __forceinline__ void operator()(const f32x4 (&acc)[2][2][4][2], const Unit& u, int wr, int wc, int fr, int fq) const {
;     ...
;         for (int ai = 0; ai < 2; ++ai) { u32x2 bs[4][2][2];
; #pragma unroll
;             for (int m = 0; m < 4; ++m)
; #pragma unroll
;                 for (int bj = 0; bj < 2; ++bj)
; #pragma unroll
;                     for (int n = 0; n < 2; ++n) bs[m][bj][n] = *(const u32x2*)(xres + (size_t)(row0 + ai * HALF + m * 16) * 1024 + col0 + bj * HALF + n * 16);
; #pragma unroll
;             for (int m = 0; m < 4; ++m) { const int row = row0 + ai * HALF + m * 16; const size_t off = (size_t)row * 1024 + col0; float ss = 0.f;
; #pragma unroll
;                 for (int bj = 0; bj < 2; ++bj)
; #pragma unroll
;                     for (int n = 0; n < 2; ++n) { const size_t o2 = off + bj * HALF + n * 16; const u32x2 b = bs[m][bj][n];
;                         const f32x4 o = (f32x4){bflo(b.x), bfhi(b.x), bflo(b.y), bfhi(b.y)} + acc[ai][bj][m][n];
;                         ss += (o[0] * o[0] + o[1] * o[1]) + (o[2] * o[2] + o[3] * o[3]);
;                         u32x2 w; w.x = cvtpk(o[0], o[1]); w.y = cvtpk(o[2], o[3]); *(u32x2*)(xres + o2) = w; }
;                 ss += __shfl_xor(ss, 16); ss += __shfl_xor(ss, 32);
;                 if (fq == 0) part[(size_t)row * 16 + u.pn * 4 + wc] = ss; }
.LBB0_860:
	s_or_b64 exec, exec, s[26:27]
	v_add_u32_e32 v102, 0x80, v138
	v_ashrrev_i32_e32 v103, 31, v102
	v_lshlrev_b64 v[108:109], 11, v[102:103]
	s_waitcnt lgkmcnt(0)
	v_lshl_add_u64 v[66:67], v[140:141], 0, v[108:109]
	global_load_dwordx2 v[110:111], v[66:67], off nt
	global_load_dwordx2 v[112:113], v[66:67], off offset:32 nt
	global_load_dwordx2 v[106:107], v[66:67], off offset:256 nt
	global_load_dwordx2 v[104:105], v[66:67], off offset:288 nt
	v_add_u32_e32 v86, 0x90, v138
	v_ashrrev_i32_e32 v87, 31, v86
	v_add_u32_e32 v68, 0xa0, v138
	v_lshlrev_b64 v[98:99], 11, v[86:87]
	v_ashrrev_i32_e32 v69, 31, v68
	v_lshl_add_u64 v[66:67], v[140:141], 0, v[98:99]
	v_lshlrev_b64 v[88:89], 11, v[68:69]
	global_load_dwordx2 v[100:101], v[66:67], off nt
	global_load_dwordx2 v[96:97], v[66:67], off offset:32 nt
	global_load_dwordx2 v[94:95], v[66:67], off offset:256 nt
	global_load_dwordx2 v[92:93], v[66:67], off offset:288 nt
	v_lshl_add_u64 v[66:67], v[140:141], 0, v[88:89]
	global_load_dwordx2 v[90:91], v[66:67], off nt
	global_load_dwordx2 v[84:85], v[66:67], off offset:32 nt
	global_load_dwordx2 v[80:81], v[66:67], off offset:256 nt
	global_load_dwordx2 v[76:77], v[66:67], off offset:288 nt
	v_add_u32_e32 v66, 0xb0, v138
	v_ashrrev_i32_e32 v67, 31, v66
	v_lshlrev_b64 v[72:73], 11, v[66:67]
	v_lshl_add_u64 v[70:71], v[140:141], 0, v[72:73]
	global_load_dwordx2 v[82:83], v[70:71], off nt
	global_load_dwordx2 v[78:79], v[70:71], off offset:32 nt
	global_load_dwordx2 v[74:75], v[70:71], off offset:256 nt
	s_nop 0
	global_load_dwordx2 v[70:71], v[70:71], off offset:288 nt
	s_waitcnt vmcnt(15)
	v_cvt_f32_f16_e32 v114, v110
	v_cvt_f32_f16_sdwa v115, v110 dst_sel:DWORD dst_unused:UNUSED_PAD src0_sel:WORD_1
	v_cvt_f32_f16_e32 v110, v111
	v_cvt_f32_f16_sdwa v111, v111 dst_sel:DWORD dst_unused:UNUSED_PAD src0_sel:WORD_1
	v_pk_add_f32 v[62:63], v[62:63], v[114:115]
	v_pk_add_f32 v[64:65], v[64:65], v[110:111]
	v_mul_f32_e32 v110, v63, v63
	v_mul_f32_e32 v111, v65, v65
	v_fmac_f32_e32 v110, v62, v62
	v_fmac_f32_e32 v111, v64, v64
	v_add_f32_e32 v114, v110, v111
	v_cvt_pk_f16_f32 v111, v64, v65
	s_waitcnt vmcnt(14)
	v_cvt_f32_f16_e32 v64, v112
	v_cvt_f32_f16_sdwa v65, v112 dst_sel:DWORD dst_unused:UNUSED_PAD src0_sel:WORD_1
	v_cvt_pk_f16_f32 v110, v62, v63
	v_lshl_add_u64 v[62:63], s[18:19], 0, v[108:109]
	v_cvt_f32_f16_e32 v108, v113
	v_cvt_f32_f16_sdwa v109, v113 dst_sel:DWORD dst_unused:UNUSED_PAD src0_sel:WORD_1
	v_pk_add_f32 v[58:59], v[58:59], v[64:65]
	v_lshl_add_u64 v[62:63], v[136:137], 1, v[62:63]
	v_mul_f32_e32 v64, v59, v59
	v_pk_add_f32 v[60:61], v[60:61], v[108:109]
	v_fmac_f32_e32 v64, v58, v58
	v_cvt_pk_f16_f32 v58, v58, v59
	v_cvt_pk_f16_f32 v59, v60, v61
	v_mul_f32_e32 v65, v61, v61
	global_store_dwordx2 v[62:63], v[58:59], off offset:32
	s_waitcnt vmcnt(14)
	v_cvt_f32_f16_e32 v58, v106
	v_cvt_f32_f16_sdwa v59, v106 dst_sel:DWORD dst_unused:UNUSED_PAD src0_sel:WORD_1
	v_fmac_f32_e32 v65, v60, v60
	v_cvt_f32_f16_e32 v60, v107
	v_cvt_f32_f16_sdwa v61, v107 dst_sel:DWORD dst_unused:UNUSED_PAD src0_sel:WORD_1
	v_pk_add_f32 v[54:55], v[54:55], v[58:59]
	v_add_f32_e32 v64, v64, v65
	v_mul_f32_e32 v58, v55, v55
	v_pk_add_f32 v[56:57], v[56:57], v[60:61]
	v_fmac_f32_e32 v58, v54, v54
	v_mul_f32_e32 v59, v57, v57
	v_cvt_pk_f16_f32 v54, v54, v55
	v_cvt_pk_f16_f32 v55, v56, v57
	v_fmac_f32_e32 v59, v56, v56
	global_store_dwordx2 v[62:63], v[54:55], off offset:256
	s_waitcnt vmcnt(14)
	v_cvt_f32_f16_e32 v54, v104
	v_cvt_f32_f16_sdwa v55, v104 dst_sel:DWORD dst_unused:UNUSED_PAD src0_sel:WORD_1
	v_cvt_f32_f16_e32 v56, v105
	v_cvt_f32_f16_sdwa v57, v105 dst_sel:DWORD dst_unused:UNUSED_PAD src0_sel:WORD_1
	v_add_f32_e32 v64, v114, v64
	v_pk_add_f32 v[50:51], v[50:51], v[54:55]
	v_add_f32_e32 v58, v58, v59
	v_pk_add_f32 v[52:53], v[52:53], v[56:57]
	v_mul_f32_e32 v54, v51, v51
	v_mul_f32_e32 v55, v53, v53
	v_fmac_f32_e32 v54, v50, v50
	v_fmac_f32_e32 v55, v52, v52
	v_add_f32_e32 v58, v64, v58
	v_add_f32_e32 v54, v54, v55
	v_add_f32_e32 v54, v58, v54
	v_cvt_pk_f16_f32 v50, v50, v51
	v_cvt_pk_f16_f32 v51, v52, v53
	global_store_dwordx2 v[62:63], v[50:51], off offset:288
	ds_bpermute_b32 v50, v210, v54
	global_store_dwordx2 v[62:63], v[110:111], off
	s_waitcnt lgkmcnt(0)
	v_add_f32_e32 v50, v54, v50
	ds_bpermute_b32 v51, v209, v50
	s_and_saveexec_b64 s[26:27], s[38:39]
	s_cbranch_execz .LBB0_862
	s_waitcnt lgkmcnt(0)
	v_add_f32_e32 v52, v50, v51
	v_lshlrev_b64 v[50:51], 6, v[102:103]
	v_lshl_add_u64 v[50:51], s[20:21], 0, v[50:51]
	v_lshl_add_u64 v[50:51], s[24:25], 2, v[50:51]
	s_lshl_b32 s70, s55, 2
	v_lshl_add_u64 v[50:51], v[50:51], 0, s[70:71]
	global_store_dword v[50:51], v52, off

; __device__ __forceinline__ unsigned cvtpk(float lo, float hi) { f32x2_t v = {lo, hi}; f16x2_t b = __builtin_convertvector(v, f16x2_t); return __builtin_bit_cast(unsigned, b); }
; __device__ __forceinline__ float bflo(unsigned w) { const f16x2_t b = __builtin_bit_cast(f16x2_t, w); return (float)b[0]; }
; __device__ __forceinline__ float bfhi(unsigned w) { const f16x2_t b = __builtin_bit_cast(f16x2_t, w); return (float)b[1]; }
;     __device__ __forceinline__ void operator()(const f32x4 (&acc)[2][2][4][2], const Unit& u, int wr, int wc, int fr, int fq) const {
;         const int row0 = u.pm * BM + wr * 64 + fr, col0 = u.pn * BM + wc * 32 + 4 * fq;
; #pragma unroll
;         for (int ai = 0; ai < 2; ++ai) { u32x2 bs[4][2][2];
; #pragma unroll
;             for (int m = 0; m < 4; ++m)
; #pragma unroll
;                 for (int bj = 0; bj < 2; ++bj)
; #pragma unroll
;                     for (int n = 0; n < 2; ++n) bs[m][bj][n] = *(const u32x2*)(xres + (size_t)(row0 + ai * HALF + m * 16) * 1024 + col0 + bj * HALF + n * 16);
; #pragma unroll
;             for (int m = 0; m < 4; ++m) { const int row = row0 + ai * HALF + m * 16; const size_t off = (size_t)row * 1024 + col0; float ss = 0.f;
; #pragma unroll
;                 for (int bj = 0; bj < 2; ++bj)
; #pragma unroll
;                     for (int n = 0; n < 2; ++n) { const size_t o2 = off + bj * HALF + n * 16; const u32x2 b = bs[m][bj][n];
;                         const f32x4 o = (f32x4){bflo(b.x), bfhi(b.x), bflo(b.y), bfhi(b.y)} + acc[ai][bj][m][n];
;                         ss += (o[0] * o[0] + o[1] * o[1]) + (o[2] * o[2] + o[3] * o[3]);
;                         u32x2 w; w.x = cvtpk(o[0], o[1]); w.y = cvtpk(o[2], o[3]); *(u32x2*)(xres + o2) = w; }
;                 ss += __shfl_xor(ss, 16); ss += __shfl_xor(ss, 32);
;                 if (fq == 0) part[(size_t)row * 16 + u.pn * 4 + wc] = ss; }
.LBB0_1066:
	v_and_b32_e32 v140, 64, v233
	v_xor_b32_e32 v139, 16, v233
	v_add_u32_e32 v140, 64, v140
	v_cmp_lt_i32_e32 vcc, v139, v140
	v_lshl_or_b32 v136, s24, 8, v207
	v_lshl_add_u32 v138, s46, 8, v179
	v_cndmask_b32_e32 v139, v233, v139, vcc
	v_lshlrev_b32_e32 v210, 2, v139
	v_xor_b32_e32 v139, 32, v233
	v_cmp_lt_i32_e32 vcc, v139, v140
	v_ashrrev_i32_e32 v137, 31, v136
	v_readlane_b32 s26, v253, 9
	v_cndmask_b32_e32 v139, v233, v139, vcc
	v_lshlrev_b32_e32 v209, 2, v139
	v_lshlrev_b64 v[202:203], 1, v[136:137]
	v_readlane_b32 s27, v253, 10
	v_ashrrev_i32_e32 v139, 31, v138
	v_lshlrev_b64 v[204:205], 11, v[138:139]
	v_lshl_add_u64 v[140:141], s[26:27], 0, v[202:203]
	v_lshl_add_u64 v[142:143], v[140:141], 0, v[204:205]
	global_load_dwordx2 v[172:173], v[142:143], off nt
	global_load_dwordx2 v[200:201], v[142:143], off offset:32 nt
	global_load_dwordx2 v[198:199], v[142:143], off offset:256 nt
	global_load_dwordx2 v[196:197], v[142:143], off offset:288 nt
	v_or_b32_e32 v180, 16, v138
	v_ashrrev_i32_e32 v181, 31, v180
	v_or_b32_e32 v146, 32, v138
	v_lshlrev_b64 v[192:193], 11, v[180:181]
	v_ashrrev_i32_e32 v147, 31, v146
	v_lshl_add_u64 v[142:143], v[140:141], 0, v[192:193]
	v_lshlrev_b64 v[182:183], 11, v[146:147]
	global_load_dwordx2 v[194:195], v[142:143], off nt
	global_load_dwordx2 v[190:191], v[142:143], off offset:32 nt
	global_load_dwordx2 v[188:189], v[142:143], off offset:256 nt
	global_load_dwordx2 v[186:187], v[142:143], off offset:288 nt
	v_lshl_add_u64 v[142:143], v[140:141], 0, v[182:183]
	global_load_dwordx2 v[184:185], v[142:143], off nt
	global_load_dwordx2 v[160:161], v[142:143], off offset:32 nt
	global_load_dwordx2 v[156:157], v[142:143], off offset:256 nt
	global_load_dwordx2 v[152:153], v[142:143], off offset:288 nt
	v_or_b32_e32 v142, 48, v138
	v_ashrrev_i32_e32 v143, 31, v142
	v_lshlrev_b64 v[148:149], 11, v[142:143]
	v_lshl_add_u64 v[144:145], v[140:141], 0, v[148:149]
	global_load_dwordx2 v[158:159], v[144:145], off nt
	global_load_dwordx2 v[154:155], v[144:145], off offset:32 nt
	global_load_dwordx2 v[150:151], v[144:145], off offset:256 nt
	s_nop 0
	global_load_dwordx2 v[144:145], v[144:145], off offset:288 nt
	s_lshl_b32 s24, s24, 2
	s_ashr_i32 s25, s24, 31
	s_waitcnt vmcnt(0)
	v_cvt_f32_f16_e32 v212, v172
	v_cvt_f32_f16_sdwa v213, v172 dst_sel:DWORD dst_unused:UNUSED_PAD src0_sel:WORD_1
	v_cvt_f32_f16_e32 v172, v173
	v_cvt_f32_f16_sdwa v173, v173 dst_sel:DWORD dst_unused:UNUSED_PAD src0_sel:WORD_1
	v_pk_add_f32 v[126:127], v[126:127], v[212:213]
	v_pk_add_f32 v[128:129], v[128:129], v[172:173]
	v_mul_f32_e32 v172, v127, v127
	v_mul_f32_e32 v173, v129, v129
	v_fmac_f32_e32 v172, v126, v126
	v_fmac_f32_e32 v173, v128, v128
	v_add_f32_e32 v174, v172, v173
	v_cvt_pk_f16_f32 v172, v126, v127
	v_lshl_add_u64 v[126:127], s[26:27], 0, v[204:205]
	v_cvt_pk_f16_f32 v173, v128, v129
	v_lshl_add_u64 v[126:127], v[126:127], 0, v[202:203]
	v_cvt_f32_f16_e32 v128, v200
	v_cvt_f32_f16_sdwa v129, v200 dst_sel:DWORD dst_unused:UNUSED_PAD src0_sel:WORD_1
	global_store_dwordx2 v[126:127], v[172:173], off
	v_cvt_f32_f16_e32 v172, v201
	v_cvt_f32_f16_sdwa v173, v201 dst_sel:DWORD dst_unused:UNUSED_PAD src0_sel:WORD_1
	v_pk_add_f32 v[122:123], v[122:123], v[128:129]
	v_pk_add_f32 v[124:125], v[124:125], v[172:173]
	v_mul_f32_e32 v128, v123, v123
	v_fmac_f32_e32 v128, v122, v122
	v_cvt_pk_f16_f32 v122, v122, v123
	v_cvt_pk_f16_f32 v123, v124, v125
	v_mul_f32_e32 v129, v125, v125
	global_store_dwordx2 v[126:127], v[122:123], off offset:32
	v_cvt_f32_f16_e32 v122, v198
	v_cvt_f32_f16_sdwa v123, v198 dst_sel:DWORD dst_unused:UNUSED_PAD src0_sel:WORD_1
	v_fmac_f32_e32 v129, v124, v124
	v_cvt_f32_f16_e32 v124, v199
	v_cvt_f32_f16_sdwa v125, v199 dst_sel:DWORD dst_unused:UNUSED_PAD src0_sel:WORD_1
	v_pk_add_f32 v[118:119], v[118:119], v[122:123]
	v_add_f32_e32 v128, v128, v129
	v_mul_f32_e32 v122, v119, v119
	v_pk_add_f32 v[120:121], v[120:121], v[124:125]
	v_fmac_f32_e32 v122, v118, v118
	v_mul_f32_e32 v123, v121, v121
	v_cvt_pk_f16_f32 v118, v118, v119
	v_cvt_pk_f16_f32 v119, v120, v121
	v_fmac_f32_e32 v123, v120, v120
	global_store_dwordx2 v[126:127], v[118:119], off offset:256
	v_cvt_f32_f16_e32 v118, v196
	v_cvt_f32_f16_sdwa v119, v196 dst_sel:DWORD dst_unused:UNUSED_PAD src0_sel:WORD_1
	v_cvt_f32_f16_e32 v120, v197
	v_cvt_f32_f16_sdwa v121, v197 dst_sel:DWORD dst_unused:UNUSED_PAD src0_sel:WORD_1
	v_add_f32_e32 v128, v174, v128
	v_pk_add_f32 v[114:115], v[114:115], v[118:119]
	v_add_f32_e32 v122, v122, v123
	v_pk_add_f32 v[116:117], v[116:117], v[120:121]
	v_mul_f32_e32 v118, v115, v115
	v_mul_f32_e32 v119, v117, v117
	v_fmac_f32_e32 v118, v114, v114
	v_fmac_f32_e32 v119, v116, v116
	v_add_f32_e32 v122, v128, v122
	v_add_f32_e32 v118, v118, v119
	v_add_f32_e32 v118, v122, v118
	v_cvt_pk_f16_f32 v114, v114, v115
	v_cvt_pk_f16_f32 v115, v116, v117
	global_store_dwordx2 v[126:127], v[114:115], off offset:288
	ds_bpermute_b32 v114, v210, v118
	s_waitcnt lgkmcnt(0)
	v_add_f32_e32 v114, v118, v114
	ds_bpermute_b32 v115, v209, v114
	s_and_saveexec_b64 s[26:27], s[38:39]
	v_readlane_b32 s76, v253, 5
	v_readlane_b32 s77, v253, 6
	v_readlane_b32 s78, v253, 7
	v_readlane_b32 s79, v253, 8
	s_mov_b32 s30, 0x8000
	s_mov_b32 s31, s65
	s_cbranch_execz .LBB0_1068
	v_readlane_b32 s28, v253, 15
	s_waitcnt lgkmcnt(0)
	v_add_f32_e32 v116, v114, v115
	v_lshlrev_b64 v[114:115], 6, v[138:139]
	v_readlane_b32 s29, v253, 16
	s_lshl_b32 s70, s55, 2
	s_nop 0
	v_lshl_add_u64 v[114:115], s[28:29], 0, v[114:115]
	v_lshl_add_u64 v[114:115], s[24:25], 2, v[114:115]
	v_lshl_add_u64 v[114:115], v[114:115], 0, s[70:71]
	global_store_dword v[114:115], v116, off

; __device__ __forceinline__ unsigned cvtpk(float lo, float hi) { f32x2_t v = {lo, hi}; f16x2_t b = __builtin_convertvector(v, f16x2_t); return __builtin_bit_cast(unsigned, b); }
; __device__ __forceinline__ float bflo(unsigned w) { const f16x2_t b = __builtin_bit_cast(f16x2_t, w); return (float)b[0]; }
; __device__ __forceinline__ float bfhi(unsigned w) { const f16x2_t b = __builtin_bit_cast(f16x2_t, w); return (float)b[1]; }
;     __device__ __forceinline__ void operator()(const f32x4 (&acc)[2][2][4][2], const Unit& u, int wr, int wc, int fr, int fq) const {
;     ...
;         for (int ai = 0; ai < 2; ++ai) { u32x2 bs[4][2][2];
; #pragma unroll
;             for (int m = 0; m < 4; ++m)
; #pragma unroll
;                 for (int bj = 0; bj < 2; ++bj)
; #pragma unroll
;                     for (int n = 0; n < 2; ++n) bs[m][bj][n] = *(const u32x2*)(xres + (size_t)(row0 + ai * HALF + m * 16) * 1024 + col0 + bj * HALF + n * 16);
; #pragma unroll
;             for (int m = 0; m < 4; ++m) { const int row = row0 + ai * HALF + m * 16; const size_t off = (size_t)row * 1024 + col0; float ss = 0.f;
; #pragma unroll
;                 for (int bj = 0; bj < 2; ++bj)
; #pragma unroll
;                     for (int n = 0; n < 2; ++n) { const size_t o2 = off + bj * HALF + n * 16; const u32x2 b = bs[m][bj][n];
;                         const f32x4 o = (f32x4){bflo(b.x), bfhi(b.x), bflo(b.y), bfhi(b.y)} + acc[ai][bj][m][n];
;                         ss += (o[0] * o[0] + o[1] * o[1]) + (o[2] * o[2] + o[3] * o[3]);
;                         u32x2 w; w.x = cvtpk(o[0], o[1]); w.y = cvtpk(o[2], o[3]); *(u32x2*)(xres + o2) = w; }
;                 ss += __shfl_xor(ss, 16); ss += __shfl_xor(ss, 32);
;                 if (fq == 0) part[(size_t)row * 16 + u.pn * 4 + wc] = ss; }
.LBB0_1074:
	s_or_b64 exec, exec, s[26:27]
	v_add_u32_e32 v102, 0x80, v138
	v_ashrrev_i32_e32 v103, 31, v102
	v_lshlrev_b64 v[108:109], 11, v[102:103]
	s_waitcnt lgkmcnt(0)
	v_lshl_add_u64 v[66:67], v[140:141], 0, v[108:109]
	global_load_dwordx2 v[110:111], v[66:67], off nt
	global_load_dwordx2 v[112:113], v[66:67], off offset:32 nt
	global_load_dwordx2 v[106:107], v[66:67], off offset:256 nt
	global_load_dwordx2 v[104:105], v[66:67], off offset:288 nt
	v_add_u32_e32 v86, 0x90, v138
	v_ashrrev_i32_e32 v87, 31, v86
	v_add_u32_e32 v70, 0xa0, v138
	v_lshlrev_b64 v[98:99], 11, v[86:87]
	v_ashrrev_i32_e32 v71, 31, v70
	v_lshl_add_u64 v[66:67], v[140:141], 0, v[98:99]
	v_lshlrev_b64 v[88:89], 11, v[70:71]
	global_load_dwordx2 v[100:101], v[66:67], off nt
	global_load_dwordx2 v[96:97], v[66:67], off offset:32 nt
	global_load_dwordx2 v[94:95], v[66:67], off offset:256 nt
	global_load_dwordx2 v[92:93], v[66:67], off offset:288 nt
	v_lshl_add_u64 v[66:67], v[140:141], 0, v[88:89]
	global_load_dwordx2 v[90:91], v[66:67], off nt
	global_load_dwordx2 v[84:85], v[66:67], off offset:32 nt
	global_load_dwordx2 v[80:81], v[66:67], off offset:256 nt
	global_load_dwordx2 v[76:77], v[66:67], off offset:288 nt
	v_add_u32_e32 v66, 0xb0, v138
	v_ashrrev_i32_e32 v67, 31, v66
	v_lshlrev_b64 v[72:73], 11, v[66:67]
	v_lshl_add_u64 v[68:69], v[140:141], 0, v[72:73]
	global_load_dwordx2 v[82:83], v[68:69], off nt
	global_load_dwordx2 v[78:79], v[68:69], off offset:32 nt
	global_load_dwordx2 v[74:75], v[68:69], off offset:256 nt
	s_nop 0
	global_load_dwordx2 v[68:69], v[68:69], off offset:288 nt
	v_readlane_b32 s26, v253, 9
	v_readlane_b32 s27, v253, 10
	s_waitcnt vmcnt(15)
	v_cvt_f32_f16_e32 v114, v110
	v_cvt_f32_f16_sdwa v115, v110 dst_sel:DWORD dst_unused:UNUSED_PAD src0_sel:WORD_1
	v_cvt_f32_f16_e32 v110, v111
	v_cvt_f32_f16_sdwa v111, v111 dst_sel:DWORD dst_unused:UNUSED_PAD src0_sel:WORD_1
	v_pk_add_f32 v[62:63], v[62:63], v[114:115]
	v_pk_add_f32 v[64:65], v[64:65], v[110:111]
	v_mul_f32_e32 v110, v63, v63
	v_mul_f32_e32 v111, v65, v65
	v_fmac_f32_e32 v110, v62, v62
	v_fmac_f32_e32 v111, v64, v64
	v_add_f32_e32 v114, v110, v111
	v_cvt_pk_f16_f32 v111, v64, v65
	s_waitcnt vmcnt(14)
	v_cvt_f32_f16_e32 v64, v112
	v_cvt_f32_f16_sdwa v65, v112 dst_sel:DWORD dst_unused:UNUSED_PAD src0_sel:WORD_1
	v_cvt_pk_f16_f32 v110, v62, v63
	v_lshl_add_u64 v[62:63], s[26:27], 0, v[108:109]
	v_cvt_f32_f16_e32 v108, v113
	v_cvt_f32_f16_sdwa v109, v113 dst_sel:DWORD dst_unused:UNUSED_PAD src0_sel:WORD_1
	v_pk_add_f32 v[58:59], v[58:59], v[64:65]
	v_lshl_add_u64 v[62:63], v[136:137], 1, v[62:63]
	v_mul_f32_e32 v64, v59, v59
	v_pk_add_f32 v[60:61], v[60:61], v[108:109]
	v_fmac_f32_e32 v64, v58, v58
	v_cvt_pk_f16_f32 v58, v58, v59
	v_cvt_pk_f16_f32 v59, v60, v61
	v_mul_f32_e32 v65, v61, v61
	global_store_dwordx2 v[62:63], v[58:59], off offset:32
	s_waitcnt vmcnt(14)
	v_cvt_f32_f16_e32 v58, v106
	v_cvt_f32_f16_sdwa v59, v106 dst_sel:DWORD dst_unused:UNUSED_PAD src0_sel:WORD_1
	v_fmac_f32_e32 v65, v60, v60
	v_cvt_f32_f16_e32 v60, v107
	v_cvt_f32_f16_sdwa v61, v107 dst_sel:DWORD dst_unused:UNUSED_PAD src0_sel:WORD_1
	v_pk_add_f32 v[54:55], v[54:55], v[58:59]
	v_add_f32_e32 v64, v64, v65
	v_mul_f32_e32 v58, v55, v55
	v_pk_add_f32 v[56:57], v[56:57], v[60:61]
	v_fmac_f32_e32 v58, v54, v54
	v_mul_f32_e32 v59, v57, v57
	v_cvt_pk_f16_f32 v54, v54, v55
	v_cvt_pk_f16_f32 v55, v56, v57
	v_fmac_f32_e32 v59, v56, v56
	global_store_dwordx2 v[62:63], v[54:55], off offset:256
	s_waitcnt vmcnt(14)
	v_cvt_f32_f16_e32 v54, v104
	v_cvt_f32_f16_sdwa v55, v104 dst_sel:DWORD dst_unused:UNUSED_PAD src0_sel:WORD_1
	v_cvt_f32_f16_e32 v56, v105
	v_cvt_f32_f16_sdwa v57, v105 dst_sel:DWORD dst_unused:UNUSED_PAD src0_sel:WORD_1
	v_add_f32_e32 v64, v114, v64
	v_pk_add_f32 v[50:51], v[50:51], v[54:55]
	v_add_f32_e32 v58, v58, v59
	v_pk_add_f32 v[52:53], v[52:53], v[56:57]
	v_mul_f32_e32 v54, v51, v51
	v_mul_f32_e32 v55, v53, v53
	v_fmac_f32_e32 v54, v50, v50
	v_fmac_f32_e32 v55, v52, v52
	v_add_f32_e32 v58, v64, v58
	v_add_f32_e32 v54, v54, v55
	v_add_f32_e32 v54, v58, v54
	v_cvt_pk_f16_f32 v50, v50, v51
	v_cvt_pk_f16_f32 v51, v52, v53
	global_store_dwordx2 v[62:63], v[50:51], off offset:288
	ds_bpermute_b32 v50, v210, v54
	global_store_dwordx2 v[62:63], v[110:111], off
	s_waitcnt lgkmcnt(0)
	v_add_f32_e32 v50, v54, v50
	ds_bpermute_b32 v51, v209, v50
	s_and_saveexec_b64 s[26:27], s[38:39]
	s_cbranch_execz .LBB0_1076
	v_readlane_b32 s28, v253, 15
	s_waitcnt lgkmcnt(0)
	v_add_f32_e32 v52, v50, v51
	v_lshlrev_b64 v[50:51], 6, v[102:103]
	v_readlane_b32 s29, v253, 16
	s_lshl_b32 s70, s55, 2
	s_nop 0
	v_lshl_add_u64 v[50:51], s[28:29], 0, v[50:51]
	v_lshl_add_u64 v[50:51], s[24:25], 2, v[50:51]
	v_lshl_add_u64 v[50:51], v[50:51], 0, s[70:71]
	global_store_dword v[50:51], v52, off
